# v33: v32 + P5 o_inter: 16 LDS fragment reads through five rotating register quads
# baseline (speedup 1.0000x reference)
; #define LAS __attribute__((address_space(3)))
; DI unsigned pk2(float lo, float hi) { f32x2 v = {lo, hi}; bfv2 b = __builtin_convertvector(v, bfv2); return __builtin_bit_cast(unsigned, b); }
; DI bf16_t f2bf(float x) { return (bf16_t)(pk2(x, 0.f) & 0xffffu); }
; #define MFMA16(a, b, c) __builtin_amdgcn_mfma_f32_16x16x32_bf16((a), (b), (c), 0, 0, 0)
; template <bool OUT> DI void hgrn_item(LAS unsigned char* lds, bf16_t* proj, float* hst, float* hdv, const float* normw, int item, bool dry) {
;     ...
;                 for (int r = 0; r < 4; ++r) { const int tt = 16 * ti + 4 * rq + r, ss = 16 * sj + e16; Ab[tt * TP + ss] = (sj <= ti && ss <= tt) ? f2bf(a[r]) : (bf16_t)0; }
;             }
; #pragma unroll
;             for (int ti = 0; ti < 4; ++ti) { o[ti] = (f32x4){0.f, 0.f, 0.f, 0.f};
; #pragma unroll
;                 for (int ks = 0; ks < 4; ++ks) { const LAS bf16_t* qp = Qt + (16 * ti + e16) * QP + 32 * ks + 4 * rq; const u32x2 q0 = *(const LAS u32x2*)qp, q1 = *(const LAS u32x2*)(qp + 16);
;                     u32x4 qa = {q0.x, q0.y, q1.x, q1.y};
;                     u32x4 sb; sb.x = pk2(st[2 * ks][0], st[2 * ks][1]); sb.y = pk2(st[2 * ks][2], st[2 * ks][3]); sb.z = pk2(st[2 * ks + 1][0], st[2 * ks + 1][1]); sb.w = pk2(st[2 * ks + 1][2], st[2 * ks + 1][3]);
;                     o[ti] = MFMA16(__builtin_bit_cast(bf16x8, qa), __builtin_bit_cast(bf16x8, sb), o[ti]); } }
;         }
; #pragma unroll
;         for (int dt = 0; dt < 8; ++dt) {
; #pragma unroll
;             for (int ks = 0; ks < 2; ++ks) { const bf16x8 ka = *(const LAS bf16x8*)(KtT + (16 * dt + e16) * TP + 32 * ks + 8 * rq); st[dt] = MFMA16(ka, vfr[ks], st[dt]); }
;             const f32x4 dv = *(const LAS f32x4*)(Dv + 16 * dt + 4 * rq);
;             st[dt] *= dv;
;         }
.LBB0_1170:
	v_or_b32_e32 v56, s14, v104
	v_cmp_gt_u32_e32 vcc, v120, v56
	s_or_b64 s[36:37], s[20:21], vcc
	s_nop 3
	v_cvt_pk_bf16_f32 v50, v50, s0
	v_cndmask_b32_e64 v50, v50, 0, s[36:37]
	v_mad_u64_u32 v[54:55], s[36:37], v56, s39, v[92:93]
	ds_write_b16 v54, v50
	v_or_b32_e32 v50, 1, v56
	v_cmp_gt_u32_e32 vcc, v120, v50
	s_or_b64 s[36:37], s[20:21], vcc
	v_cvt_pk_bf16_f32 v50, v51, s0
	v_cndmask_b32_e64 v50, v50, 0, s[36:37]
	ds_write_b16 v54, v50 offset:144
	v_or_b32_e32 v50, 2, v56
	v_cmp_gt_u32_e32 vcc, v120, v50
	s_or_b64 s[36:37], s[20:21], vcc
	v_cvt_pk_bf16_f32 v50, v52, s0
	v_cndmask_b32_e64 v50, v50, 0, s[36:37]
	ds_write_b16 v54, v50 offset:288
	v_or_b32_e32 v50, 3, v56
	v_cmp_gt_u32_e32 vcc, v120, v50
	s_or_b64 s[36:37], s[20:21], vcc
	v_cvt_pk_bf16_f32 v50, v53, s0
	v_cndmask_b32_e64 v50, v50, 0, s[36:37]
	ds_write_b16 v54, v50 offset:432
	v_add_u32_e32 v240, 0x1000, v115
	v_add_u32_e32 v241, 0x2000, v115
	v_add_u32_e32 v143, 0x3000, v115
	ds_read2_b64 v[162:165], v115 offset1:4
	ds_read2_b64 v[166:169], v115 offset0:8 offset1:12
	ds_read2_b64 v[170:173], v115 offset0:16 offset1:20
	ds_read2_b64 v[174:177], v115 offset0:24 offset1:28
	ds_read2_b64 v[178:181], v240 offset0:32 offset1:36
	s_waitcnt vmcnt(7)
	v_cvt_pk_bf16_f32 v66, v6, v7
	v_cvt_pk_bf16_f32 v67, v8, v9
	s_waitcnt vmcnt(6)
	v_cvt_pk_bf16_f32 v68, v10, v11
	v_cvt_pk_bf16_f32 v69, v12, v13
	s_waitcnt vmcnt(5)
	v_cvt_pk_bf16_f32 v70, v2, v3
	v_cvt_pk_bf16_f32 v71, v4, v5
	s_waitcnt vmcnt(4)
	v_cvt_pk_bf16_f32 v72, v18, v19
	v_cvt_pk_bf16_f32 v73, v20, v21
	s_waitcnt vmcnt(3)
	v_cvt_pk_bf16_f32 v100, v14, v15
	v_cvt_pk_bf16_f32 v101, v16, v17
	s_waitcnt vmcnt(2)
	v_cvt_pk_bf16_f32 v102, v26, v27
	v_cvt_pk_bf16_f32 v103, v28, v29
	s_waitcnt vmcnt(1)
	v_cvt_pk_bf16_f32 v144, v22, v23
	v_cvt_pk_bf16_f32 v145, v24, v25
	s_waitcnt vmcnt(0)
	v_cvt_pk_bf16_f32 v146, v30, v31
	v_cvt_pk_bf16_f32 v147, v32, v33
	s_waitcnt lgkmcnt(4)
	v_mfma_f32_16x16x32_bf16 v[50:53], v[162:165], v[66:69], 0
	ds_read2_b64 v[162:165], v240 offset0:40 offset1:44
	s_waitcnt lgkmcnt(4)
	v_mfma_f32_16x16x32_bf16 v[50:53], v[166:169], v[70:73], v[50:53]
	ds_read2_b64 v[166:169], v240 offset0:48 offset1:52
	s_waitcnt lgkmcnt(4)
	v_mfma_f32_16x16x32_bf16 v[50:53], v[170:173], v[100:103], v[50:53]
	ds_read2_b64 v[170:173], v240 offset0:56 offset1:60
	s_waitcnt lgkmcnt(4)
	v_mfma_f32_16x16x32_bf16 v[54:57], v[174:177], v[144:147], v[50:53]
	s_nop 4
	ds_read2_b64 v[174:177], v241 offset0:64 offset1:68
	s_waitcnt lgkmcnt(4)
	v_mfma_f32_16x16x32_bf16 v[50:53], v[178:181], v[66:69], 0
	ds_read2_b64 v[178:181], v241 offset0:72 offset1:76
	s_waitcnt lgkmcnt(4)
	v_mfma_f32_16x16x32_bf16 v[50:53], v[162:165], v[70:73], v[50:53]
	ds_read2_b64 v[162:165], v241 offset0:80 offset1:84
	s_waitcnt lgkmcnt(4)
	v_mfma_f32_16x16x32_bf16 v[50:53], v[166:169], v[100:103], v[50:53]
	ds_read2_b64 v[166:169], v241 offset0:88 offset1:92
	s_waitcnt lgkmcnt(4)
	v_mfma_f32_16x16x32_bf16 v[58:61], v[170:173], v[144:147], v[50:53]
	s_nop 4
	ds_read2_b64 v[170:173], v143 offset0:96 offset1:100
	s_waitcnt lgkmcnt(4)
	v_mfma_f32_16x16x32_bf16 v[50:53], v[174:177], v[66:69], 0
	ds_read2_b64 v[174:177], v143 offset0:104 offset1:108
	s_waitcnt lgkmcnt(4)
	v_mfma_f32_16x16x32_bf16 v[50:53], v[178:181], v[70:73], v[50:53]
	ds_read2_b64 v[178:181], v143 offset0:112 offset1:116
	s_waitcnt lgkmcnt(4)
	v_mfma_f32_16x16x32_bf16 v[50:53], v[162:165], v[100:103], v[50:53]
	ds_read2_b64 v[162:165], v143 offset0:120 offset1:124
	s_waitcnt lgkmcnt(4)
	v_mfma_f32_16x16x32_bf16 v[62:65], v[166:169], v[144:147], v[50:53]
	s_nop 4
	s_waitcnt lgkmcnt(3)
	v_mfma_f32_16x16x32_bf16 v[50:53], v[170:173], v[66:69], 0
	s_waitcnt lgkmcnt(2)
	v_mfma_f32_16x16x32_bf16 v[50:53], v[174:177], v[70:73], v[50:53]
	s_waitcnt lgkmcnt(1)
	v_mfma_f32_16x16x32_bf16 v[50:53], v[178:181], v[100:103], v[50:53]
	s_waitcnt lgkmcnt(0)
	v_mfma_f32_16x16x32_bf16 v[70:73], v[162:165], v[144:147], v[50:53]
	v_lshl_add_u64 v[102:103], v[98:99], 0, s[34:35]
	v_lshl_add_u64 v[100:101], v[96:97], 0, s[34:35]
	v_add_u32_e32 v66, v93, v108
	s_nop 1
	v_add_u32_e32 v67, 0x13c00, v93
	ds_read_b128 v[50:53], v66 offset:34816
	ds_read_b128 v[162:165], v66 offset:34880
	ds_read_b128 v[166:169], v67
	s_add_u32 s34, s34, 0xc8000
	s_addc_u32 s35, s35, 0
	s_cmp_lg_u32 s34, 0x320000
	ds_read_b128 v[170:173], v66 offset:37120
	ds_read_b128 v[174:177], v66 offset:37184
	ds_read_b128 v[178:181], v67 offset:64
	s_waitcnt lgkmcnt(3)
	v_mfma_f32_16x16x32_bf16 v[6:9], v[50:53], v[46:49], v[6:9]
	v_mfma_f32_16x16x32_bf16 v[6:9], v[162:165], v[42:45], v[6:9]
	s_nop 7
	v_pk_mul_f32 v[8:9], v[8:9], v[168:169]
	v_pk_mul_f32 v[6:7], v[6:7], v[166:167]
	ds_read_b128 v[50:53], v66 offset:39424
	ds_read_b128 v[162:165], v66 offset:39488
	ds_read_b128 v[166:169], v67 offset:128
	s_waitcnt lgkmcnt(3)
	v_mfma_f32_16x16x32_bf16 v[10:13], v[170:173], v[46:49], v[10:13]
	v_mfma_f32_16x16x32_bf16 v[10:13], v[174:177], v[42:45], v[10:13]
	s_nop 7
	v_pk_mul_f32 v[12:13], v[12:13], v[180:181]
	v_pk_mul_f32 v[10:11], v[10:11], v[178:179]
	ds_read_b128 v[170:173], v66 offset:41728
	ds_read_b128 v[174:177], v66 offset:41792
	ds_read_b128 v[178:181], v67 offset:192
	s_waitcnt lgkmcnt(3)
	v_mfma_f32_16x16x32_bf16 v[2:5], v[50:53], v[46:49], v[2:5]
	v_mfma_f32_16x16x32_bf16 v[2:5], v[162:165], v[42:45], v[2:5]
	s_nop 7
	v_pk_mul_f32 v[4:5], v[4:5], v[168:169]
	v_pk_mul_f32 v[2:3], v[2:3], v[166:167]
	ds_read_b128 v[50:53], v66 offset:44032
	ds_read_b128 v[162:165], v66 offset:44096
	ds_read_b128 v[166:169], v67 offset:256
	s_waitcnt lgkmcnt(3)
; #define LAS __attribute__((address_space(3)))
; #define MFMA16(a, b, c) __builtin_amdgcn_mfma_f32_16x16x32_bf16((a), (b), (c), 0, 0, 0)
; template <bool OUT> DI void hgrn_item(LAS unsigned char* lds, bf16_t* proj, float* hst, float* hdv, const float* normw, int item, bool dry) {
;     ...
;         for (int dt = 0; dt < 8; ++dt) {
; #pragma unroll
;             for (int ks = 0; ks < 2; ++ks) { const bf16x8 ka = *(const LAS bf16x8*)(KtT + (16 * dt + e16) * TP + 32 * ks + 8 * rq); st[dt] = MFMA16(ka, vfr[ks], st[dt]); }
;             const f32x4 dv = *(const LAS f32x4*)(Dv + 16 * dt + 4 * rq);
;             st[dt] *= dv;
;         }
;         u32x4 gate8[2];
;         if (OUT) {
; #pragma unroll
;             for (int j = 0; j < 2; ++j) { const int cch = tid + 512 * j; gate8[j] = *(const u32x4*)(proj + (row0 + (cch >> 4)) * NPJ + C_HG + h * 128 + 8 * (cch & 15)); }
;         }
;         __syncthreads();
;         if (OUT) {
; #pragma unroll
;             for (int ti = 0; ti < 4; ++ti)
; #pragma unroll
;                 for (int ks = 0; ks < 2; ++ks) if (2 * ks <= ti) { const bf16x8 aa = *(const LAS bf16x8*)(Ab + (16 * ti + e16) * TP + 32 * ks + 8 * rq); o[ti] = MFMA16(aa, vfr[ks], o[ti]); }
;             LAS float* Ob = (LAS float*)(lds + HOB_OFF);
; #pragma unroll
;             for (int ti = 0; ti < 4; ++ti)
; #pragma unroll
;                 for (int r = 0; r < 4; ++r) Ob[(16 * ti + 4 * rq + r) * OBP + w * 16 + e16] = o[ti][r];
	v_mfma_f32_16x16x32_bf16 v[18:21], v[170:173], v[46:49], v[18:21]
	v_mfma_f32_16x16x32_bf16 v[18:21], v[174:177], v[42:45], v[18:21]
	s_nop 7
	v_pk_mul_f32 v[20:21], v[20:21], v[180:181]
	v_pk_mul_f32 v[18:19], v[18:19], v[178:179]
	ds_read_b128 v[170:173], v66 offset:46336
	ds_read_b128 v[174:177], v66 offset:46400
	ds_read_b128 v[178:181], v67 offset:320
	s_waitcnt lgkmcnt(3)
	v_mfma_f32_16x16x32_bf16 v[14:17], v[50:53], v[46:49], v[14:17]
	v_mfma_f32_16x16x32_bf16 v[14:17], v[162:165], v[42:45], v[14:17]
	s_nop 7
	v_pk_mul_f32 v[16:17], v[16:17], v[168:169]
	v_pk_mul_f32 v[14:15], v[14:15], v[166:167]
	ds_read_b128 v[50:53], v66 offset:48640
	ds_read_b128 v[162:165], v66 offset:48704
	ds_read_b128 v[166:169], v67 offset:384
	s_waitcnt lgkmcnt(3)
	v_mfma_f32_16x16x32_bf16 v[26:29], v[170:173], v[46:49], v[26:29]
	v_mfma_f32_16x16x32_bf16 v[26:29], v[174:177], v[42:45], v[26:29]
	s_nop 7
	v_pk_mul_f32 v[28:29], v[28:29], v[180:181]
	v_pk_mul_f32 v[26:27], v[26:27], v[178:179]
	ds_read_b128 v[170:173], v66 offset:50944
	ds_read_b128 v[174:177], v66 offset:51008
	ds_read_b128 v[178:181], v67 offset:448
	s_waitcnt lgkmcnt(3)
	v_mfma_f32_16x16x32_bf16 v[22:25], v[50:53], v[46:49], v[22:25]
	v_mfma_f32_16x16x32_bf16 v[22:25], v[162:165], v[42:45], v[22:25]
	s_nop 7
	v_pk_mul_f32 v[24:25], v[24:25], v[168:169]
	v_pk_mul_f32 v[22:23], v[22:23], v[166:167]
	s_waitcnt lgkmcnt(0)
	v_mfma_f32_16x16x32_bf16 v[30:33], v[170:173], v[46:49], v[30:33]
	v_mfma_f32_16x16x32_bf16 v[30:33], v[174:177], v[42:45], v[30:33]
	s_nop 7
	v_pk_mul_f32 v[32:33], v[32:33], v[180:181]
	v_pk_mul_f32 v[30:31], v[30:31], v[178:179]
	v_add_co_u32_e32 v50, vcc, s47, v102
	s_nop 0
	v_addc_co_u32_e32 v51, vcc, 0, v103, vcc
	global_load_dwordx4 v[66:69], v[50:51], off offset:512
	v_add_co_u32_e32 v50, vcc, s47, v100
	s_nop 1
	v_addc_co_u32_e32 v51, vcc, 0, v101, vcc
	global_load_dwordx4 v[50:53], v[50:51], off offset:512
	s_barrier
	ds_read_b128 v[144:147], v116
	ds_read_b128 v[162:165], v116 offset:2304
	ds_read_b128 v[166:169], v116 offset:4608
	ds_read_b128 v[170:173], v116 offset:4672
	ds_read_b128 v[174:177], v116 offset:6912
	ds_read_b128 v[178:181], v116 offset:6976
	s_waitcnt lgkmcnt(5)
	v_mfma_f32_16x16x32_bf16 v[54:57], v[144:147], v[46:49], v[54:57]
	s_waitcnt lgkmcnt(4)
	v_mfma_f32_16x16x32_bf16 v[58:61], v[162:165], v[46:49], v[58:61]
	s_waitcnt lgkmcnt(3)
	v_mfma_f32_16x16x32_bf16 v[62:65], v[166:169], v[46:49], v[62:65]
	s_waitcnt lgkmcnt(2)
	v_mfma_f32_16x16x32_bf16 v[62:65], v[170:173], v[42:45], v[62:65]
	s_waitcnt lgkmcnt(1)
	v_mfma_f32_16x16x32_bf16 v[46:49], v[174:177], v[46:49], v[70:73]
	s_nop 2
	ds_write2_b32 v125, v54, v55 offset1:132
	s_waitcnt lgkmcnt(1)
	v_mfma_f32_16x16x32_bf16 v[42:45], v[178:181], v[42:45], v[46:49]
	s_nop 2
	v_add_u32_e32 v46, 0x400, v125
	ds_write2_b32 v46, v56, v57 offset0:8 offset1:140
	v_add_u32_e32 v46, 0x2000, v125
	ds_write2_b32 v46, v58, v59 offset0:64 offset1:196
	v_add_u32_e32 v46, 0x2400, v125
	ds_write2_b32 v46, v60, v61 offset0:72 offset1:204
	v_add_u32_e32 v46, 0x4200, v125
	ds_write2_b32 v46, v62, v63 offset1:132
	v_add_u32_e32 v46, 0x4600, v125
	ds_write2_b32 v46, v64, v65 offset0:8 offset1:140
	v_add_u32_e32 v46, 0x6200, v125
	ds_write2_b32 v46, v42, v43 offset0:64 offset1:196
	v_add_u32_e32 v42, 0x6600, v125
	ds_write2_b32 v42, v44, v45 offset0:72 offset1:204
	s_waitcnt lgkmcnt(0)
	s_barrier
; #define LAS __attribute__((address_space(3)))
; DI float bflo(unsigned w) { return __uint_as_float(w << 16); }
; DI float bfhi(unsigned w) { return __uint_as_float(w & 0xffff0000u); }
; DI u32x4 pack8(f32x4 a, f32x4 b) { u32x4 w; w.x = pk2(a[0], a[1]); w.y = pk2(a[2], a[3]); w.z = pk2(b[0], b[1]); w.w = pk2(b[2], b[3]); return w; }
; template <bool OUT> DI void hgrn_item(LAS unsigned char* lds, bf16_t* proj, float* hst, float* hdv, const float* normw, int item, bool dry) {
;     ...
; #pragma unroll
;             for (int j = 0; j < 2; ++j) { const int cch = tid + 512 * j, tt = cch >> 4, e0 = 8 * (cch & 15);
;                 const f32x4 a0 = *(const LAS f32x4*)(Ob + tt * OBP + e0), a1 = *(const LAS f32x4*)(Ob + tt * OBP + e0 + 4);
;                 float q = (a0[0] * a0[0] + a0[1] * a0[1]) + (a0[2] * a0[2] + a0[3] * a0[3]) + (a1[0] * a1[0] + a1[1] * a1[1]) + (a1[2] * a1[2] + a1[3] * a1[3]);
;                 q += __shfl_xor(q, 1); q += __shfl_xor(q, 2); q += __shfl_xor(q, 4); q += __shfl_xor(q, 8);
;                 const float rs = __builtin_amdgcn_rsqf(q * (1.0f / 128.0f) + 1e-6f);
;                 const f32x4 n0 = *(const f32x4*)(normw + e0), n1 = *(const f32x4*)(normw + e0 + 4); const u32x4 g = gate8[j];
;                 f32x4 y0, y1;
;                 y0[0] = a0[0] * rs * n0[0] * bflo(g.x); y0[1] = a0[1] * rs * n0[1] * bfhi(g.x); y0[2] = a0[2] * rs * n0[2] * bflo(g.y); y0[3] = a0[3] * rs * n0[3] * bfhi(g.y);
;                 y1[0] = a1[0] * rs * n1[0] * bflo(g.z); y1[1] = a1[1] * rs * n1[1] * bfhi(g.z); y1[2] = a1[2] * rs * n1[2] * bflo(g.w); y1[3] = a1[3] * rs * n1[3] * bfhi(g.w);
;                 if (!dry) *(u32x4*)(proj + (row0 + tt) * NPJ + C_HQ + h * 128 + e0) = pack8(y0, y1); }
	ds_read_b128 v[42:45], v117
	ds_read_b128 v[46:49], v117 offset:16
	s_waitcnt vmcnt(1)
	v_lshlrev_b32_e32 v64, 16, v68
	v_and_b32_e32 v65, 0xffff0000, v68
	s_waitcnt lgkmcnt(1)
	v_pk_mul_f32 v[54:55], v[44:45], v[44:45]
	v_pk_mul_f32 v[56:57], v[42:43], v[42:43]
	s_nop 0
	v_pk_mov_b32 v[58:59], v[56:57], v[54:55] op_sel:[1,0]
	v_mov_b32_e32 v57, v55
	v_pk_add_f32 v[54:55], v[58:59], v[56:57]
	s_waitcnt lgkmcnt(0)
	v_pk_mul_f32 v[56:57], v[48:49], v[48:49]
	v_pk_mul_f32 v[58:59], v[46:47], v[46:47]
	v_mov_b32_e32 v60, v56
	v_mov_b32_e32 v61, v58
	v_mov_b32_e32 v58, v57
	v_pk_add_f32 v[56:57], v[60:61], v[58:59]
	v_add_f32_e32 v54, v54, v55
	v_add_f32_e32 v54, v54, v57
	v_add_f32_e32 v54, v56, v54
	s_nop 1
	v_add_f32_dpp v54, v54, v54 quad_perm:[1,0,3,2] row_mask:0xf bank_mask:0xf
	s_nop 1
	v_add_f32_dpp v54, v54, v54 quad_perm:[2,3,0,1] row_mask:0xf bank_mask:0xf
	s_nop 1
	v_add_f32_dpp v62, v54, v54 row_half_mirror row_mask:0xf bank_mask:0xf
	s_nop 1
	v_add_f32_dpp v62, v62, v62 row_mirror row_mask:0xf bank_mask:0xf
	v_fmamk_f32 v62, v62, 0x3c000000, v118
	v_rsq_f32_e32 v62, v62
	s_nop 0
	v_pk_mul_f32 v[46:47], v[46:47], v[62:63] op_sel_hi:[1,0]
	v_pk_mul_f32 v[48:49], v[48:49], v[62:63] op_sel_hi:[1,0]
	v_pk_mul_f32 v[42:43], v[42:43], v[62:63] op_sel_hi:[1,0]
	v_pk_mul_f32 v[44:45], v[44:45], v[62:63] op_sel_hi:[1,0]
	s_waitcnt vmcnt(0)
	v_pk_mul_f32 v[42:43], v[232:233], v[42:43]
	v_pk_mul_f32 v[46:47], v[236:237], v[46:47]
	v_lshlrev_b32_e32 v58, 16, v69
	v_and_b32_e32 v59, 0xffff0000, v69
	v_pk_mul_f32 v[48:49], v[238:239], v[48:49]
	v_lshlrev_b32_e32 v54, 16, v67
	v_pk_mul_f32 v[48:49], v[48:49], v[58:59]
	v_lshlrev_b32_e32 v58, 16, v66
	v_and_b32_e32 v59, 0xffff0000, v66
	v_and_b32_e32 v55, 0xffff0000, v67
	v_pk_mul_f32 v[44:45], v[234:235], v[44:45]
	v_pk_mul_f32 v[46:47], v[46:47], v[64:65]
	v_pk_mul_f32 v[42:43], v[42:43], v[58:59]
	v_pk_mul_f32 v[44:45], v[44:45], v[54:55]
	v_cvt_pk_bf16_f32 v42, v42, v43
	v_cvt_pk_bf16_f32 v43, v44, v45
	v_cvt_pk_bf16_f32 v44, v46, v47
	v_cvt_pk_bf16_f32 v45, v48, v49
	global_store_dwordx4 v[102:103], v[42:45], off offset:1536
	ds_read_b128 v[42:45], v119
	ds_read_b128 v[46:49], v119 offset:16
	v_lshlrev_b32_e32 v64, 16, v52
	v_and_b32_e32 v65, 0xffff0000, v52
	v_lshlrev_b32_e32 v52, 16, v53
	s_waitcnt lgkmcnt(1)
	v_pk_mul_f32 v[54:55], v[44:45], v[44:45]
	v_pk_mul_f32 v[56:57], v[42:43], v[42:43]
	v_and_b32_e32 v53, 0xffff0000, v53
	v_pk_mov_b32 v[58:59], v[56:57], v[54:55] op_sel:[1,0]
	v_mov_b32_e32 v57, v55
	v_pk_add_f32 v[54:55], v[58:59], v[56:57]
	s_waitcnt lgkmcnt(0)
	v_pk_mul_f32 v[56:57], v[48:49], v[48:49]
	v_pk_mul_f32 v[58:59], v[46:47], v[46:47]
	v_mov_b32_e32 v60, v56
	v_mov_b32_e32 v61, v58
	v_mov_b32_e32 v58, v57
	v_pk_add_f32 v[56:57], v[60:61], v[58:59]
	v_add_f32_e32 v54, v54, v55
	v_add_f32_e32 v54, v54, v57
	v_add_f32_e32 v54, v56, v54
	s_nop 1
	v_add_f32_dpp v54, v54, v54 quad_perm:[1,0,3,2] row_mask:0xf bank_mask:0xf
	s_nop 1
	v_add_f32_dpp v54, v54, v54 quad_perm:[2,3,0,1] row_mask:0xf bank_mask:0xf
	s_nop 1
	v_add_f32_dpp v62, v54, v54 row_half_mirror row_mask:0xf bank_mask:0xf
	s_nop 1
	v_add_f32_dpp v62, v62, v62 row_mirror row_mask:0xf bank_mask:0xf
	v_fmamk_f32 v62, v62, 0x3c000000, v118
	v_rsq_f32_e32 v62, v62
	s_nop 0
	v_pk_mul_f32 v[48:49], v[48:49], v[62:63] op_sel_hi:[1,0]
	v_pk_mul_f32 v[46:47], v[46:47], v[62:63] op_sel_hi:[1,0]
	v_pk_mul_f32 v[42:43], v[42:43], v[62:63] op_sel_hi:[1,0]
	v_pk_mul_f32 v[44:45], v[44:45], v[62:63] op_sel_hi:[1,0]
	v_pk_mul_f32 v[42:43], v[232:233], v[42:43]
	v_pk_mul_f32 v[48:49], v[238:239], v[48:49]
	v_pk_mul_f32 v[46:47], v[236:237], v[46:47]
	v_pk_mul_f32 v[48:49], v[48:49], v[52:53]
	v_lshlrev_b32_e32 v52, 16, v50
	v_and_b32_e32 v53, 0xffff0000, v50
	v_lshlrev_b32_e32 v50, 16, v51
	v_and_b32_e32 v51, 0xffff0000, v51
	v_pk_mul_f32 v[44:45], v[234:235], v[44:45]
	v_pk_mul_f32 v[46:47], v[46:47], v[64:65]
	v_pk_mul_f32 v[42:43], v[42:43], v[52:53]
	v_pk_mul_f32 v[44:45], v[44:45], v[50:51]
	v_cvt_pk_bf16_f32 v42, v42, v43
	v_cvt_pk_bf16_f32 v43, v44, v45
	v_cvt_pk_bf16_f32 v44, v46, v47
	v_cvt_pk_bf16_f32 v45, v48, v49
	global_store_dwordx4 v[100:101], v[42:45], off offset:1536
	s_waitcnt vmcnt(1)
	v_lshl_or_b32 v129, v185, 16, v184
	v_lshl_or_b32 v127, v190, 16, v191
	v_lshl_or_b32 v131, v192, 16, v188
	v_lshl_or_b32 v128, v194, 16, v189
	v_lshl_or_b32 v133, v196, 16, v195
	v_lshl_or_b32 v135, v203, 16, v202
	v_lshl_or_b32 v134, v214, 16, v215
	v_lshl_or_b32 v34, v187, 16, v186
	v_lshl_or_b32 v35, v199, 16, v193
	v_lshl_or_b32 v36, v200, 16, v197
	v_lshl_or_b32 v130, v198, 16, v201
	v_lshl_or_b32 v37, v205, 16, v204
	v_lshl_or_b32 v132, v206, 16, v207
	v_lshl_or_b32 v137, v209, 16, v208
	v_lshl_or_b32 v38, v211, 16, v210
	v_lshl_or_b32 v139, v216, 16, v212
	v_lshl_or_b32 v136, v218, 16, v213
	v_lshl_or_b32 v141, v220, 16, v219
	v_lshl_or_b32 v39, v223, 16, v217
	v_lshl_or_b32 v40, v224, 16, v221
	v_lshl_or_b32 v138, v222, 16, v225
	v_lshl_or_b32 v142, v227, 16, v226
	v_lshl_or_b32 v41, v229, 16, v228
	v_lshl_or_b32 v140, v230, 16, v231
	v_mov_b32_e32 v46, v127
	v_mov_b32_e32 v47, v128
	v_mov_b32_e32 v49, v130
	v_mov_b32_e32 v51, v132
	v_mov_b32_e32 v52, v134
	v_mov_b32_e32 v53, v136
	v_mov_b32_e32 v54, v138
	v_mov_b32_e32 v48, v140
	v_mov_b32_e32 v42, v129
	v_mov_b32_e32 v43, v131
	v_mov_b32_e32 v44, v133
	v_mov_b32_e32 v45, v135
	v_mov_b32_e32 v50, v137
	v_mov_b32_e32 v55, v139
	v_mov_b32_e32 v56, v141
	v_mov_b32_e32 v57, v142
	s_cbranch_scc0 .LBB0_1168
